# LN stats exchange: skip acquire invalidate on normal path (partner stats are read with sc1 loads only)
# speedup vs baseline: 1.0054x; 1.0054x over previous
.LBB0_465:
	s_mov_b64 s[12:13], -1
	s_waitcnt lgkmcnt(0)
	s_mov_b64 s[22:23], 0
	s_and_saveexec_b64 s[24:25], s[12:13]
	s_cbranch_execz .LBB0_468
	s_branch .Lmy_lnx_0

.Lmy_lnx_0:
	s_and_b64 exec, exec, s[10:11]
	v_cndmask_b32_e64 v2, 0, 1, s[22:23]
	ds_write_b32 v231, v2 offset:10240

.LBB0_545:
	s_mov_b64 s[12:13], -1
	s_mov_b64 s[18:19], 0
	s_waitcnt lgkmcnt(0)
	s_and_saveexec_b64 s[20:21], s[12:13]
	s_cbranch_execz .LBB0_548
	s_branch .Lmy_lnx_1

.Lmy_lnx_1:
	s_and_b64 exec, exec, s[10:11]
	v_cndmask_b32_e64 v2, 0, 1, s[18:19]
	ds_write_b32 v231, v2 offset:10240

.LBB0_885:
	s_mov_b64 s[12:13], -1
	s_waitcnt lgkmcnt(0)
	s_mov_b64 s[20:21], 0
	s_and_saveexec_b64 s[22:23], s[12:13]
	s_cbranch_execz .LBB0_888
	s_branch .Lmy_lnx_2

.Lmy_lnx_2:
	s_and_b64 exec, exec, s[10:11]
	v_cndmask_b32_e64 v3, 0, 1, s[20:21]
	ds_write_b32 v231, v3 offset:10240

.LBB0_1053:
	s_mov_b64 s[12:13], -1
	s_mov_b64 s[16:17], 0
	s_waitcnt lgkmcnt(0)
	s_and_saveexec_b64 s[18:19], s[12:13]
	s_cbranch_execz .LBB0_1056
	s_branch .Lmy_lnx_3

.Lmy_lnx_3:
	s_and_b64 exec, exec, s[10:11]
	v_cndmask_b32_e64 v2, 0, 1, s[16:17]
	ds_write_b32 v231, v2 offset:10240
